# attention steady loops: row sums in two alternating accumulators interleaved with the bf16 packs; differential loop subtracts in place before exp; out-proj epilogue residual loads pipelined 4 groups d
# speedup vs baseline: 1.0202x; 1.0103x over previous
; __device__ __forceinline__ void phase_attn(const Params& p, int l, unsigned char* smem) {
;     const int kind = l % 3;
;     const bool need_ctx = l < 3;
;     bf16_t* sbase = (bf16_t*)smem; float* srpb = (float*)(sbase + 2 * ATT_BUF);
;     int tid = threadIdx.x; asm volatile("" : "+v"(tid));
;     const int lane = tid & 63, w = tid >> 6, lr = lane & 31, lh = lane >> 5;
;     const int b = blockIdx.x & 7, xj = blockIdx.x >> 3, xn = gridDim.x >> 3;
;     if (kind == 0) {
;     ...
;         const float lam = p.lam[0];
;         const float post = 1.0f - p.lam_init;
;         float* blk = p.scr + (size_t)blockIdx.x * (2 * 256 * 128);
;         const int nlat = 8 * 16, nctx = need_ctx ? 8 : 0;
;         for (int li = xj; li < nlat + nctx; li += xn) {
;             int hh, qb; const bool isctx = li >= nlat;
;             if (!isctx) { qb = li & 15; hh = li >> 4; } else { qb = 0; hh = li - nlat; }
;             const int qpos0 = isctx ? 0 : CTXL + qb * 256;
;             const size_t grow0 = isctx ? (size_t)MLAT + b * CTXL : (size_t)b * SEQ + qb * 256;
;             const int nt = isctx ? 4 : TT / 64;
;             const bf16_t* Va = p.vt + ((size_t)b * 16 + hh * 2) * TT * 64;
;             const bf16_t* Vb = p.vt + ((size_t)b * 16 + hh * 2 + 1) * TT * 64;
.LBB0_252:
	s_or_b64 exec, exec, s[4:5]
	v_mov_b32_e32 v210, v234
	v_readfirstlane_b32 s4, v234
	s_nop 0
	s_cmpk_lt_u32 s4, 0x100
	s_cbranch_scc1 .Lattn_prio_skip
	s_setprio 1
.Lattn_prio_skip:
	s_cmp_lt_i32 s45, 1
	s_mov_b64 s[4:5], -1
	s_barrier
	s_cbranch_scc1 .LBB0_760
	s_cmp_lg_u32 s45, 1
	s_cbranch_scc0 .LBB0_334
	v_readlane_b32 s4, v254, 60
	v_readlane_b32 s5, v254, 61
	s_and_b64 s[4:5], s[4:5], exec
	s_movk_i32 s4, 0x88
	s_cselect_b32 s34, 0x80, s4
	v_readlane_b32 s4, v254, 21
	s_movk_i32 s60, 0x1000
	s_cmp_ge_u32 s4, s34
	s_cbranch_scc1 .LBB0_333
	v_readlane_b32 s4, v253, 0
	v_readlane_b32 s18, v253, 14
	v_readlane_b32 s19, v253, 15
	v_readlane_b32 s5, v253, 1
	v_readlane_b32 s6, v253, 2
	v_readlane_b32 s7, v253, 3
	v_readlane_b32 s8, v253, 4
	v_readlane_b32 s9, v253, 5
	global_load_dword v17, v1, s[18:19]
	v_readlane_b32 s10, v253, 6
	v_readlane_b32 s11, v253, 7
	v_readlane_b32 s12, v253, 8
	v_readlane_b32 s13, v253, 9
	v_readlane_b32 s14, v253, 10
	v_readlane_b32 s15, v253, 11
	v_readlane_b32 s16, v253, 12
	v_readlane_b32 s17, v253, 13
	v_ashrrev_i32_e32 v0, 1, v210
	v_and_b32_e32 v212, 0xffffffe0, v0
	v_lshlrev_b32_e32 v0, 3, v210
	v_readlane_b32 s4, v253, 32
	v_and_b32_e32 v0, 0x1f8, v0
	v_readlane_b32 s5, v253, 33
	v_readlane_b32 s6, v253, 34
	v_readlane_b32 s7, v253, 35
	v_readlane_b32 s8, v253, 36
	v_readlane_b32 s9, v253, 37
	v_readlane_b32 s10, v253, 38
	v_readlane_b32 s11, v253, 39
	v_readlane_b32 s12, v253, 40
	v_readlane_b32 s13, v253, 41
	v_readlane_b32 s14, v253, 42
	v_readlane_b32 s15, v253, 43
	v_readlane_b32 s16, v253, 44
	v_readlane_b32 s17, v253, 45
	v_readlane_b32 s18, v253, 46
	v_readlane_b32 s19, v253, 47
	v_lshl_add_u64 v[214:215], s[12:13], 0, v[0:1]
	v_and_b32_e32 v4, 63, v210
	v_readlane_b32 s4, v254, 25
	v_lshlrev_b32_e32 v0, 2, v4
	v_readlane_b32 s5, v254, 26
	v_readlane_b32 s10, v254, 31
	v_readlane_b32 s11, v254, 32
	v_readlane_b32 s12, v254, 33
	v_readlane_b32 s13, v254, 34
	v_ashrrev_i32_e32 v213, 31, v212
	v_lshl_add_u64 v[218:219], s[10:11], 0, v[0:1]
	v_lshl_add_u64 v[216:217], s[12:13], 0, v[0:1]
	v_lshlrev_b64 v[2:3], 9, v[212:213]
	v_lshlrev_b32_e32 v0, 3, v4
	v_readlane_b32 s4, v254, 44
	v_or_b32_e32 v2, v2, v0
	v_readlane_b32 s5, v254, 45
	v_readlane_b32 s35, v254, 21
	v_readlane_b32 s6, v254, 27
	v_lshl_add_u64 v[220:221], s[4:5], 0, v[2:3]
	v_add_u32_e32 v2, 0x100, v212
	v_ashrrev_i32_e32 v3, 31, v2
	v_lshlrev_b64 v[2:3], 9, v[2:3]
	v_or_b32_e32 v2, v2, v0
	v_lshl_add_u64 v[222:223], s[4:5], 0, v[2:3]
	v_readlane_b32 s7, v254, 28
	v_readlane_b32 s8, v254, 29
	v_readlane_b32 s9, v254, 30
	v_readlane_b32 s14, v254, 35
	v_readlane_b32 s15, v254, 36
	v_readlane_b32 s16, v254, 37
	v_readlane_b32 s17, v254, 38
	v_readlane_b32 s18, v254, 39
	v_readlane_b32 s19, v254, 40

.LBB0_260:
	v_add_u32_e32 v0, s22, v251
	ds_read_b64_tr_b16 v[198:199], v0 offset:24576
	ds_read_b64_tr_b16 v[200:201], v0 offset:25088
	s_waitcnt lgkmcnt(9)
	v_mfma_f32_32x32x16_bf16 v[130:145], v[194:197], v[162:165], 0
	v_add_f32_e32 v230, v98, v99
	v_cvt_pk_bf16_f32 v150, v98, v99
	v_add_f32_e32 v231, v100, v101
	v_cvt_pk_bf16_f32 v151, v100, v101
	v_add_f32_e32 v230, v102, v230
	v_add_f32_e32 v231, v103, v231
	ds_read_b64_tr_b16 v[194:195], v0 offset:28672
	ds_read_b64_tr_b16 v[196:197], v0 offset:29184
	s_waitcnt lgkmcnt(10)
	v_mfma_f32_32x32x16_bf16 v[114:129], v[186:189], v[162:165], 0
	v_add_f32_e32 v230, v104, v230
	v_cvt_pk_bf16_f32 v152, v102, v103
	v_add_f32_e32 v231, v105, v231
	v_cvt_pk_bf16_f32 v153, v104, v105
	v_add_f32_e32 v230, v106, v230
	v_add_f32_e32 v231, v107, v231
	ds_read_b64_tr_b16 v[102:103], v0 offset:25600
	ds_read_b64_tr_b16 v[104:105], v0 offset:26112
	s_waitcnt lgkmcnt(11)
	v_mfma_f32_32x32x16_bf16 v[130:145], v[190:193], v[158:161], v[130:145]
	v_add_f32_e32 v230, v108, v230
	v_cvt_pk_bf16_f32 v10, v106, v107
	v_add_f32_e32 v231, v109, v231
	v_cvt_pk_bf16_f32 v11, v108, v109
	v_add_f32_e32 v230, v110, v230
	v_add_f32_e32 v231, v111, v231
	ds_read_b64_tr_b16 v[98:99], v0 offset:29696
	ds_read_b64_tr_b16 v[100:101], v0 offset:30208
	s_waitcnt lgkmcnt(12)
	v_mfma_f32_32x32x16_bf16 v[114:129], v[182:185], v[158:161], v[114:129]
	v_add_f32_e32 v230, v112, v230
	v_cvt_pk_bf16_f32 v12, v110, v111
	v_add_f32_e32 v231, v113, v231
	v_cvt_pk_bf16_f32 v13, v112, v113
	v_add_f32_e32 v230, v82, v230
	v_add_f32_e32 v231, v83, v231
	ds_read_b64_tr_b16 v[110:111], v0 offset:26624
	ds_read_b64_tr_b16 v[112:113], v0 offset:27136
	s_waitcnt lgkmcnt(13)
	v_mfma_f32_32x32x16_bf16 v[130:145], v[178:181], v[154:157], v[130:145]
	v_add_f32_e32 v230, v84, v230
	v_cvt_pk_bf16_f32 v6, v82, v83
	v_add_f32_e32 v231, v85, v231
	v_cvt_pk_bf16_f32 v7, v84, v85
	v_add_f32_e32 v230, v86, v230
	v_add_f32_e32 v231, v87, v231
	ds_read_b64_tr_b16 v[106:107], v0 offset:30720
	ds_read_b64_tr_b16 v[108:109], v0 offset:31232
	s_waitcnt lgkmcnt(14)
	v_mfma_f32_32x32x16_bf16 v[114:129], v[174:177], v[154:157], v[114:129]
	v_add_f32_e32 v230, v88, v230
	v_cvt_pk_bf16_f32 v8, v86, v87
	v_add_f32_e32 v231, v89, v231
	v_cvt_pk_bf16_f32 v9, v88, v89
	v_add_f32_e32 v230, v90, v230
	v_add_f32_e32 v231, v91, v231
	ds_read_b64_tr_b16 v[86:87], v0 offset:27648
	ds_read_b64_tr_b16 v[88:89], v0 offset:28160
	s_waitcnt lgkmcnt(14)
	v_mfma_f32_32x32x16_bf16 v[130:145], v[170:173], v[146:149], v[130:145]
	v_add_f32_e32 v230, v92, v230
	v_cvt_pk_bf16_f32 v2, v90, v91
	v_add_f32_e32 v231, v93, v231
	v_cvt_pk_bf16_f32 v3, v92, v93
	v_add_f32_e32 v230, v94, v230
	v_add_f32_e32 v231, v95, v231
	ds_read_b64_tr_b16 v[82:83], v0 offset:31744
	ds_read_b64_tr_b16 v[84:85], v0 offset:32256
	v_mfma_f32_32x32x16_bf16 v[114:129], v[166:169], v[146:149], v[114:129]
	v_add_f32_e32 v230, v96, v230
	v_cvt_pk_bf16_f32 v4, v94, v95
	v_add_f32_e32 v231, v97, v231
	v_cvt_pk_bf16_f32 v5, v96, v97
	s_add_u32 s54, s48, s14
	s_addc_u32 s55, s49, s15
	s_add_u32 s56, s54, 0x8000
	s_addc_u32 s57, s55, 0
	s_add_i32 s16, s21, s43
	s_mov_b32 m0, s16
	s_nop 0
	global_load_lds_dwordx4 v208, s[56:57]
	s_add_u32 s56, s50, s14
	s_addc_u32 s57, s51, s15
	s_add_u32 s56, s56, 0x4000
	s_addc_u32 s57, s57, 0
	s_add_i32 s16, s13, s44
	s_mov_b32 m0, s16
	s_nop 0
	global_load_lds_dwordx4 v209, s[56:57]
	s_add_u32 s58, s52, s14
	s_addc_u32 s59, s53, s15
	s_add_u32 s58, s58, 0x4000
	s_addc_u32 s59, s59, 0
	s_add_i32 s16, s13, s45
	s_mov_b32 m0, s16
	s_nop 0
	global_load_lds_dwordx4 v209, s[58:59]
	v_add_f32_e32 v230, v230, v231
	v_add_f32_e32 v206, v232, v230
	v_max3_f32 v90, v130, v131, v132
	v_max3_f32 v90, v90, v133, v134
	v_max3_f32 v91, v114, v115, v116
	v_max3_f32 v90, v90, v135, v136
	v_max3_f32 v91, v91, v117, v118
	v_max3_f32 v90, v90, v137, v138
	v_max3_f32 v91, v91, v119, v120
	v_max3_f32 v90, v90, v139, v140
	v_max3_f32 v91, v91, v121, v122
	v_max3_f32 v90, v90, v141, v142
	v_max3_f32 v91, v91, v123, v124
	v_max3_f32 v90, v90, v143, v144
	v_max3_f32 v91, v91, v125, v126
	v_max3_f32 v91, v91, v127, v128
	v_max3_f32 v90, v90, v145, v129
	v_max_f32_e32 v0, v90, v91
	v_mov_b32_e32 v90, v0
	s_nop 1
	v_permlane32_swap_b32_e32 v0, v90
	v_max_f32_e32 v0, v0, v90
	v_sub_f32_e32 v0, v0, v248
	v_cmp_lt_f32_e32 vcc, s84, v0
	s_cmp_lg_u64 vcc, 0
	s_cselect_b64 s[16:17], -1, 0
	s_cbranch_vccnz .LBB0_268
.LBB0_261:
	v_add_u32_e32 v0, s22, v249
	v_add_u32_e32 v166, 0xe800, v0
	s_waitcnt lgkmcnt(14)
	v_mfma_f32_32x32x16_bf16 v[66:81], v[150:153], v[198:201], v[66:81]
	v_sub_f32_e32 v130, v130, v248
	v_sub_f32_e32 v131, v131, v248
	v_exp_f32_e32 v130, v130
	v_exp_f32_e32 v131, v131
	ds_read_b64_tr_b16 v[90:91], v0 offset:59392
	ds_read_b64_tr_b16 v[92:93], v0 offset:59904
	s_waitcnt lgkmcnt(14)
	v_mfma_f32_32x32x16_bf16 v[50:65], v[150:153], v[194:197], v[50:65]
	v_sub_f32_e32 v132, v132, v248
	v_sub_f32_e32 v133, v133, v248
	v_exp_f32_e32 v132, v132
	v_exp_f32_e32 v133, v133
	ds_read_b64_tr_b16 v[94:95], v0 offset:63488
	ds_read_b64_tr_b16 v[96:97], v0 offset:64000
	s_waitcnt lgkmcnt(14)
	v_mfma_f32_32x32x16_bf16 v[66:81], v[10:13], v[102:105], v[66:81]
	v_sub_f32_e32 v134, v134, v248
	v_sub_f32_e32 v135, v135, v248
	v_exp_f32_e32 v134, v134
	v_exp_f32_e32 v135, v135
	ds_read_b64_tr_b16 v[102:103], v0 offset:60416
	ds_read_b64_tr_b16 v[104:105], v0 offset:60928
	s_waitcnt lgkmcnt(14)
	v_mfma_f32_32x32x16_bf16 v[50:65], v[10:13], v[98:101], v[50:65]
	v_sub_f32_e32 v136, v136, v248
	v_sub_f32_e32 v137, v137, v248
	v_exp_f32_e32 v136, v136
	v_exp_f32_e32 v137, v137
	ds_read_b64_tr_b16 v[98:99], v0 offset:64512
	ds_read_b64_tr_b16 v[100:101], v0 offset:65024
	s_waitcnt lgkmcnt(14)
	v_mfma_f32_32x32x16_bf16 v[66:81], v[6:9], v[110:113], v[66:81]
	v_sub_f32_e32 v138, v138, v248
	v_sub_f32_e32 v139, v139, v248
	v_exp_f32_e32 v138, v138
	v_exp_f32_e32 v139, v139
	ds_read_b64_tr_b16 v[110:111], v0 offset:61440
	ds_read_b64_tr_b16 v[112:113], v0 offset:61952
	s_waitcnt lgkmcnt(14)
	v_mfma_f32_32x32x16_bf16 v[50:65], v[6:9], v[106:109], v[50:65]
	v_sub_f32_e32 v140, v140, v248
	v_sub_f32_e32 v141, v141, v248
	v_exp_f32_e32 v140, v140
	v_exp_f32_e32 v141, v141
	ds_read_b64_tr_b16 v[106:107], v166 offset:6144
	ds_read_b64_tr_b16 v[108:109], v166 offset:6656
	s_waitcnt lgkmcnt(14)
	v_mfma_f32_32x32x16_bf16 v[66:81], v[2:5], v[86:89], v[66:81]
	v_sub_f32_e32 v142, v142, v248
	v_sub_f32_e32 v143, v143, v248
	v_exp_f32_e32 v142, v142
	v_exp_f32_e32 v143, v143
	ds_read_b64_tr_b16 v[190:191], v0 offset:62464
	ds_read_b64_tr_b16 v[192:193], v0 offset:62976
	s_waitcnt lgkmcnt(14)
	v_mfma_f32_32x32x16_bf16 v[50:65], v[2:5], v[82:85], v[50:65]
	v_sub_f32_e32 v144, v144, v248
	v_sub_f32_e32 v145, v145, v248
	v_exp_f32_e32 v144, v144
	v_exp_f32_e32 v145, v145
	ds_read_b64_tr_b16 v[194:195], v166 offset:7168
	ds_read_b64_tr_b16 v[196:197], v166 offset:7680
	s_waitcnt lgkmcnt(14)
	v_mfma_f32_32x32x16_bf16 v[34:49], v[150:153], v[90:93], v[34:49]
	v_sub_f32_e32 v114, v114, v248
	v_sub_f32_e32 v115, v115, v248
	v_exp_f32_e32 v114, v114
	v_exp_f32_e32 v115, v115
	s_waitcnt lgkmcnt(12)
	v_mfma_f32_32x32x16_bf16 v[18:33], v[150:153], v[94:97], v[18:33]
	v_sub_f32_e32 v116, v116, v248
	v_sub_f32_e32 v117, v117, v248
	v_exp_f32_e32 v116, v116
	v_exp_f32_e32 v117, v117
	v_add_u32_e32 v0, s13, v250
	ds_read_b128 v[86:89], v0
	ds_read_b128 v[82:85], v0 offset:512
	s_waitcnt lgkmcnt(12)
	v_mfma_f32_32x32x16_bf16 v[34:49], v[10:13], v[102:105], v[34:49]
	v_sub_f32_e32 v118, v118, v248
	v_sub_f32_e32 v119, v119, v248
	v_exp_f32_e32 v118, v118
	v_exp_f32_e32 v119, v119
	ds_read_b128 v[186:189], v0 offset:2048
	ds_read_b128 v[182:185], v0 offset:2560
	s_waitcnt lgkmcnt(12)
	v_mfma_f32_32x32x16_bf16 v[18:33], v[10:13], v[98:101], v[18:33]
	v_sub_f32_e32 v120, v120, v248
	v_sub_f32_e32 v121, v121, v248
	v_exp_f32_e32 v120, v120
	v_exp_f32_e32 v121, v121
	ds_read_b128 v[178:181], v0 offset:4096
	ds_read_b128 v[174:177], v0 offset:4608
	s_waitcnt lgkmcnt(12)
	v_mfma_f32_32x32x16_bf16 v[34:49], v[6:9], v[110:113], v[34:49]
	v_sub_f32_e32 v122, v122, v248
	v_sub_f32_e32 v123, v123, v248
	v_exp_f32_e32 v122, v122
	v_exp_f32_e32 v123, v123
	ds_read_b128 v[170:173], v0 offset:6144
	ds_read_b128 v[166:169], v0 offset:6656
	s_waitcnt lgkmcnt(12)
	v_mfma_f32_32x32x16_bf16 v[18:33], v[6:9], v[106:109], v[18:33]
	v_sub_f32_e32 v124, v124, v248
	v_sub_f32_e32 v125, v125, v248
	v_exp_f32_e32 v124, v124
	v_exp_f32_e32 v125, v125
	s_waitcnt lgkmcnt(10)
	v_mfma_f32_32x32x16_bf16 v[34:49], v[2:5], v[190:193], v[34:49]
	v_sub_f32_e32 v126, v126, v248
	v_sub_f32_e32 v127, v127, v248
	v_exp_f32_e32 v126, v126
	v_exp_f32_e32 v127, v127
	s_waitcnt lgkmcnt(8)
	v_mfma_f32_32x32x16_bf16 v[18:33], v[2:5], v[194:197], v[18:33]
	v_sub_f32_e32 v128, v128, v248
	v_sub_f32_e32 v129, v129, v248
	v_exp_f32_e32 v128, v128
	v_exp_f32_e32 v129, v129
	s_waitcnt vmcnt(3) lgkmcnt(0)
	s_barrier
	s_andn2_b64 vcc, exec, s[16:17]
	v_add_u32_e32 v0, s33, v252
	s_cbranch_vccnz .LBB0_263
	s_waitcnt lgkmcnt(0)
	ds_read_b128 v[90:93], v0 offset:49248
	ds_read_b128 v[94:97], v0 offset:49216
	ds_read_b128 v[98:101], v0 offset:49184
	ds_read_b128 v[102:105], v0 offset:49152
	s_waitcnt lgkmcnt(3)
	v_pk_mul_f32 v[78:79], v[78:79], v[90:91]
	s_waitcnt lgkmcnt(2)
	v_pk_mul_f32 v[74:75], v[74:75], v[94:95]
	s_waitcnt lgkmcnt(1)
	v_pk_mul_f32 v[70:71], v[70:71], v[98:99]
	v_pk_mul_f32 v[80:81], v[80:81], v[92:93]
	v_pk_mul_f32 v[76:77], v[76:77], v[96:97]
	v_pk_mul_f32 v[72:73], v[72:73], v[100:101]
	s_waitcnt lgkmcnt(0)
	v_pk_mul_f32 v[68:69], v[68:69], v[104:105]
	v_pk_mul_f32 v[66:67], v[66:67], v[102:103]
	v_pk_mul_f32 v[62:63], v[62:63], v[90:91]
	v_pk_mul_f32 v[58:59], v[58:59], v[94:95]
	v_pk_mul_f32 v[54:55], v[54:55], v[98:99]
	v_pk_mul_f32 v[64:65], v[64:65], v[92:93]
	v_pk_mul_f32 v[60:61], v[60:61], v[96:97]
	v_pk_mul_f32 v[56:57], v[56:57], v[100:101]
	v_pk_mul_f32 v[52:53], v[52:53], v[104:105]
	v_pk_mul_f32 v[50:51], v[50:51], v[102:103]
	v_pk_mul_f32 v[46:47], v[46:47], v[90:91]
	v_pk_mul_f32 v[42:43], v[42:43], v[94:95]
	v_pk_mul_f32 v[38:39], v[38:39], v[98:99]
	v_pk_mul_f32 v[48:49], v[48:49], v[92:93]
	v_pk_mul_f32 v[44:45], v[44:45], v[96:97]
	v_pk_mul_f32 v[40:41], v[40:41], v[100:101]
	v_pk_mul_f32 v[36:37], v[36:37], v[104:105]
	v_pk_mul_f32 v[34:35], v[34:35], v[102:103]
	v_pk_mul_f32 v[30:31], v[30:31], v[90:91]
	v_pk_mul_f32 v[26:27], v[26:27], v[94:95]
	v_pk_mul_f32 v[22:23], v[22:23], v[98:99]
	v_pk_mul_f32 v[32:33], v[32:33], v[92:93]
	v_pk_mul_f32 v[28:29], v[28:29], v[96:97]
	v_pk_mul_f32 v[24:25], v[24:25], v[100:101]
	v_pk_mul_f32 v[20:21], v[20:21], v[104:105]
	v_pk_mul_f32 v[18:19], v[18:19], v[102:103]
.LBB0_263:
	s_add_i32 s16, s13, 0x2000
	s_cmpk_lg_i32 s13, 0x4000
	s_cselect_b32 s47, s16, 0
	v_add_u32_e32 v207, s21, v251
	ds_read_b64_tr_b16 v[198:199], v207 offset:24576
	ds_read_b64_tr_b16 v[200:201], v207 offset:25088
	s_waitcnt lgkmcnt(9)
	v_mfma_f32_32x32x16_bf16 v[98:113], v[86:89], v[162:165], 0
	v_add_f32_e32 v230, v130, v131
	v_cvt_pk_bf16_f32 v150, v130, v131
	v_add_f32_e32 v231, v132, v133
	v_cvt_pk_bf16_f32 v151, v132, v133
	v_add_f32_e32 v230, v134, v230
	v_add_f32_e32 v231, v135, v231
	ds_read_b64_tr_b16 v[194:195], v207 offset:28672
	ds_read_b64_tr_b16 v[196:197], v207 offset:29184
	s_waitcnt lgkmcnt(10)
	v_mfma_f32_32x32x16_bf16 v[82:97], v[82:85], v[162:165], 0
	v_add_f32_e32 v230, v136, v230
	v_cvt_pk_bf16_f32 v152, v134, v135
	v_add_f32_e32 v231, v137, v231
	v_cvt_pk_bf16_f32 v153, v136, v137
	v_add_f32_e32 v230, v138, v230
	v_add_f32_e32 v231, v139, v231
	ds_read_b64_tr_b16 v[190:191], v207 offset:25600
	ds_read_b64_tr_b16 v[192:193], v207 offset:26112
	s_waitcnt lgkmcnt(11)
	v_mfma_f32_32x32x16_bf16 v[98:113], v[186:189], v[158:161], v[98:113]
	v_add_f32_e32 v230, v140, v230
	v_cvt_pk_bf16_f32 v10, v138, v139
	v_add_f32_e32 v231, v141, v231
	v_cvt_pk_bf16_f32 v11, v140, v141
	v_add_f32_e32 v230, v142, v230
	v_add_f32_e32 v231, v143, v231
	ds_read_b64_tr_b16 v[138:139], v207 offset:29696
	ds_read_b64_tr_b16 v[140:141], v207 offset:30208
	s_waitcnt lgkmcnt(12)
	v_mfma_f32_32x32x16_bf16 v[82:97], v[182:185], v[158:161], v[82:97]
	v_add_f32_e32 v230, v144, v230
	v_cvt_pk_bf16_f32 v12, v142, v143
	v_add_f32_e32 v231, v145, v231
	v_cvt_pk_bf16_f32 v13, v144, v145
	v_add_f32_e32 v230, v114, v230
	v_add_f32_e32 v231, v115, v231
	ds_read_b64_tr_b16 v[134:135], v207 offset:26624
	ds_read_b64_tr_b16 v[136:137], v207 offset:27136
	s_waitcnt lgkmcnt(13)
	v_mfma_f32_32x32x16_bf16 v[98:113], v[178:181], v[154:157], v[98:113]
	v_add_f32_e32 v230, v116, v230
	v_cvt_pk_bf16_f32 v6, v114, v115
	v_add_f32_e32 v231, v117, v231
	v_cvt_pk_bf16_f32 v7, v116, v117
	v_add_f32_e32 v230, v118, v230
	v_add_f32_e32 v231, v119, v231
	ds_read_b64_tr_b16 v[130:131], v207 offset:30720
	ds_read_b64_tr_b16 v[132:133], v207 offset:31232
	s_waitcnt lgkmcnt(14)
	v_mfma_f32_32x32x16_bf16 v[82:97], v[174:177], v[154:157], v[82:97]
	v_add_f32_e32 v230, v120, v230
	v_cvt_pk_bf16_f32 v8, v118, v119
	v_add_f32_e32 v231, v121, v231
	v_cvt_pk_bf16_f32 v9, v120, v121
	v_add_f32_e32 v230, v122, v230
	v_add_f32_e32 v231, v123, v231
	ds_read_b64_tr_b16 v[118:119], v207 offset:27648
	ds_read_b64_tr_b16 v[120:121], v207 offset:28160
	s_waitcnt lgkmcnt(14)
	v_mfma_f32_32x32x16_bf16 v[98:113], v[170:173], v[146:149], v[98:113]
	v_add_f32_e32 v230, v124, v230
	v_cvt_pk_bf16_f32 v2, v122, v123
	v_add_f32_e32 v231, v125, v231
	v_cvt_pk_bf16_f32 v3, v124, v125
	v_add_f32_e32 v230, v126, v230
	v_add_f32_e32 v231, v127, v231
	ds_read_b64_tr_b16 v[114:115], v207 offset:31744
	ds_read_b64_tr_b16 v[116:117], v207 offset:32256
	v_mfma_f32_32x32x16_bf16 v[82:97], v[166:169], v[146:149], v[82:97]
	v_add_f32_e32 v230, v128, v230
	v_cvt_pk_bf16_f32 v4, v126, v127
	v_add_f32_e32 v231, v129, v231
	v_cvt_pk_bf16_f32 v5, v128, v129
	s_add_u32 s56, s54, 0xa000
	s_addc_u32 s57, s55, 0
	s_add_i32 s16, s13, s43
	s_mov_b32 m0, s16
	s_nop 0
	global_load_lds_dwordx4 v208, s[56:57]
	s_add_u32 s56, s50, s14
	s_addc_u32 s57, s51, s15
	s_add_u32 s56, s56, 0x6000
	s_addc_u32 s57, s57, 0
	s_add_i32 s16, s47, s44
	s_mov_b32 m0, s16
	s_nop 0
	global_load_lds_dwordx4 v209, s[56:57]
	s_add_u32 s58, s52, s14
	s_addc_u32 s59, s53, s15
	s_add_u32 s58, s58, 0x6000
	s_addc_u32 s59, s59, 0
	s_add_i32 s16, s47, s45
	s_mov_b32 m0, s16
	s_nop 0
	global_load_lds_dwordx4 v209, s[58:59]
	v_max3_f32 v14, v98, v99, v100
	v_max3_f32 v14, v14, v101, v102
	v_max3_f32 v15, v82, v83, v84
	v_max3_f32 v14, v14, v103, v104
	v_max3_f32 v15, v15, v85, v86
	v_max3_f32 v14, v14, v105, v106
	v_max3_f32 v15, v15, v87, v88
	v_max3_f32 v14, v14, v107, v108
	v_max3_f32 v15, v15, v89, v90
	v_max3_f32 v14, v14, v109, v110
	v_max3_f32 v15, v15, v91, v92
	v_max3_f32 v14, v14, v111, v112
	v_max3_f32 v15, v15, v93, v94
	v_max3_f32 v15, v15, v95, v96
	v_max3_f32 v14, v14, v113, v97
	v_max_f32_e32 v14, v14, v15
	v_mov_b32_e32 v15, v14
	s_nop 1
	v_permlane32_swap_b32_e32 v14, v15
	v_max_f32_e32 v14, v14, v15
	v_sub_f32_e32 v14, v14, v248
	v_cmp_lt_f32_e32 vcc, s84, v14
	s_cmp_lg_u64 vcc, 0
	v_add_f32_e32 v230, v230, v231
	v_add_f32_e32 v232, v206, v230
	s_cselect_b64 s[16:17], -1, 0
	s_cbranch_vccnz .LBB0_271
;   #define WB(a,b) do{ if constexpr(DV2){WAIT_BAR(b);} else {WAIT_BAR(a);} }while(0)
;   #define RESC() do{ if(resc){ asm volatile("s_waitcnt lgkmcnt(0)":::"memory"); \
;       _Pragma("unroll") for(int d_=0;d_<ND;++d_) _Pragma("unroll") for(int r=0;r<16;++r)o[d_][r]*=wsf[crow(r,hi)]; } }while(0)
;   #define ROT() do{sl_prev=sl_cur;sl_cur=sl_next;sl_next=(sl_next==(NSLOT-1)*SLOTB)?0:sl_next+SLOTB;}while(0)
;     ...
;   int t=1;
;   for(;t+5<NT;t+=2){
;     STEP(pB0,pB1,pA0,pA1,t,true,true,true);     WB(2,3); RESC(); ROT();
.LBB0_264:
	v_add_u32_e32 v14, s21, v249
	v_add_u32_e32 v15, 0xe800, v14
	s_waitcnt lgkmcnt(14)
	v_mfma_f32_32x32x16_bf16 v[66:81], v[150:153], v[198:201], v[66:81]
	v_sub_f32_e32 v98, v98, v248
	v_sub_f32_e32 v99, v99, v248
	v_exp_f32_e32 v98, v98
	v_exp_f32_e32 v99, v99
	ds_read_b64_tr_b16 v[122:123], v14 offset:59392
	ds_read_b64_tr_b16 v[124:125], v14 offset:59904
	s_waitcnt lgkmcnt(14)
	v_mfma_f32_32x32x16_bf16 v[50:65], v[150:153], v[194:197], v[50:65]
	v_sub_f32_e32 v100, v100, v248
	v_sub_f32_e32 v101, v101, v248
	v_exp_f32_e32 v100, v100
	v_exp_f32_e32 v101, v101
	ds_read_b64_tr_b16 v[126:127], v14 offset:63488
	ds_read_b64_tr_b16 v[128:129], v14 offset:64000
	s_waitcnt lgkmcnt(14)
	v_mfma_f32_32x32x16_bf16 v[66:81], v[10:13], v[190:193], v[66:81]
	v_sub_f32_e32 v102, v102, v248
	v_sub_f32_e32 v103, v103, v248
	v_exp_f32_e32 v102, v102
	v_exp_f32_e32 v103, v103
	ds_read_b64_tr_b16 v[142:143], v14 offset:60416
	ds_read_b64_tr_b16 v[144:145], v14 offset:60928
	s_waitcnt lgkmcnt(14)
	v_mfma_f32_32x32x16_bf16 v[50:65], v[10:13], v[138:141], v[50:65]
	v_sub_f32_e32 v104, v104, v248
	v_sub_f32_e32 v105, v105, v248
	v_exp_f32_e32 v104, v104
	v_exp_f32_e32 v105, v105
	ds_read_b64_tr_b16 v[138:139], v14 offset:64512
	ds_read_b64_tr_b16 v[140:141], v14 offset:65024
	s_waitcnt lgkmcnt(14)
	v_mfma_f32_32x32x16_bf16 v[66:81], v[6:9], v[134:137], v[66:81]
	v_sub_f32_e32 v106, v106, v248
	v_sub_f32_e32 v107, v107, v248
	v_exp_f32_e32 v106, v106
	v_exp_f32_e32 v107, v107
	ds_read_b64_tr_b16 v[134:135], v14 offset:61440
	ds_read_b64_tr_b16 v[136:137], v14 offset:61952
	s_waitcnt lgkmcnt(14)
	v_mfma_f32_32x32x16_bf16 v[50:65], v[6:9], v[130:133], v[50:65]
	v_sub_f32_e32 v108, v108, v248
	v_sub_f32_e32 v109, v109, v248
	v_exp_f32_e32 v108, v108
	v_exp_f32_e32 v109, v109
	ds_read_b64_tr_b16 v[130:131], v15 offset:6144
	ds_read_b64_tr_b16 v[132:133], v15 offset:6656
	s_waitcnt lgkmcnt(14)
	v_mfma_f32_32x32x16_bf16 v[66:81], v[2:5], v[118:121], v[66:81]
	v_sub_f32_e32 v110, v110, v248
	v_sub_f32_e32 v111, v111, v248
	v_exp_f32_e32 v110, v110
	v_exp_f32_e32 v111, v111
	ds_read_b64_tr_b16 v[118:119], v14 offset:62464
	ds_read_b64_tr_b16 v[120:121], v14 offset:62976
	s_waitcnt lgkmcnt(14)
	v_mfma_f32_32x32x16_bf16 v[50:65], v[2:5], v[114:117], v[50:65]
	v_sub_f32_e32 v112, v112, v248
	v_sub_f32_e32 v113, v113, v248
	v_exp_f32_e32 v112, v112
	v_exp_f32_e32 v113, v113
	ds_read_b64_tr_b16 v[114:115], v15 offset:7168
	ds_read_b64_tr_b16 v[116:117], v15 offset:7680
	s_waitcnt lgkmcnt(14)
	v_mfma_f32_32x32x16_bf16 v[34:49], v[150:153], v[122:125], v[34:49]
	v_sub_f32_e32 v82, v82, v248
	v_sub_f32_e32 v83, v83, v248
	v_exp_f32_e32 v82, v82
	v_exp_f32_e32 v83, v83
	s_waitcnt lgkmcnt(12)
	v_mfma_f32_32x32x16_bf16 v[18:33], v[150:153], v[126:129], v[18:33]
	v_sub_f32_e32 v84, v84, v248
	v_sub_f32_e32 v85, v85, v248
	v_exp_f32_e32 v84, v84
	v_exp_f32_e32 v85, v85
	v_add_u32_e32 v14, s47, v250
	ds_read_b128 v[194:197], v14
	ds_read_b128 v[186:189], v14 offset:512
	s_waitcnt lgkmcnt(12)
	v_mfma_f32_32x32x16_bf16 v[34:49], v[10:13], v[142:145], v[34:49]
	v_sub_f32_e32 v86, v86, v248
	v_sub_f32_e32 v87, v87, v248
	v_exp_f32_e32 v86, v86
	v_exp_f32_e32 v87, v87
	ds_read_b128 v[190:193], v14 offset:2048
	ds_read_b128 v[182:185], v14 offset:2560
	s_waitcnt lgkmcnt(12)
	v_mfma_f32_32x32x16_bf16 v[18:33], v[10:13], v[138:141], v[18:33]
	v_sub_f32_e32 v88, v88, v248
	v_sub_f32_e32 v89, v89, v248
	v_exp_f32_e32 v88, v88
	v_exp_f32_e32 v89, v89
	ds_read_b128 v[178:181], v14 offset:4096
	ds_read_b128 v[174:177], v14 offset:4608
	s_waitcnt lgkmcnt(12)
	v_mfma_f32_32x32x16_bf16 v[34:49], v[6:9], v[134:137], v[34:49]
	v_sub_f32_e32 v90, v90, v248
	v_sub_f32_e32 v91, v91, v248
	v_exp_f32_e32 v90, v90
	v_exp_f32_e32 v91, v91
	ds_read_b128 v[170:173], v14 offset:6144
	ds_read_b128 v[166:169], v14 offset:6656
	s_waitcnt lgkmcnt(12)
	v_mfma_f32_32x32x16_bf16 v[18:33], v[6:9], v[130:133], v[18:33]
	v_sub_f32_e32 v92, v92, v248
	v_sub_f32_e32 v93, v93, v248
	v_exp_f32_e32 v92, v92
	v_exp_f32_e32 v93, v93
	s_waitcnt lgkmcnt(10)
	v_mfma_f32_32x32x16_bf16 v[34:49], v[2:5], v[118:121], v[34:49]
	v_sub_f32_e32 v94, v94, v248
	v_sub_f32_e32 v95, v95, v248
	v_exp_f32_e32 v94, v94
	v_exp_f32_e32 v95, v95
	s_waitcnt lgkmcnt(8)
	v_mfma_f32_32x32x16_bf16 v[18:33], v[2:5], v[114:117], v[18:33]
	v_sub_f32_e32 v96, v96, v248
	v_sub_f32_e32 v97, v97, v248
	v_exp_f32_e32 v96, v96
	v_exp_f32_e32 v97, v97
	s_waitcnt vmcnt(3) lgkmcnt(0)
	s_barrier
	s_andn2_b64 vcc, exec, s[16:17]
	s_cbranch_vccnz .LBB0_266
	s_waitcnt lgkmcnt(0)
	ds_read_b128 v[114:117], v0 offset:49248
	ds_read_b128 v[118:121], v0 offset:49216
	ds_read_b128 v[122:125], v0 offset:49184
	ds_read_b128 v[126:129], v0 offset:49152
	s_waitcnt lgkmcnt(3)
	v_pk_mul_f32 v[78:79], v[78:79], v[114:115]
	s_waitcnt lgkmcnt(2)
	v_pk_mul_f32 v[74:75], v[74:75], v[118:119]
	s_waitcnt lgkmcnt(1)
	v_pk_mul_f32 v[70:71], v[70:71], v[122:123]
	v_pk_mul_f32 v[80:81], v[80:81], v[116:117]
	v_pk_mul_f32 v[76:77], v[76:77], v[120:121]
	v_pk_mul_f32 v[72:73], v[72:73], v[124:125]
	s_waitcnt lgkmcnt(0)
	v_pk_mul_f32 v[68:69], v[68:69], v[128:129]
	v_pk_mul_f32 v[66:67], v[66:67], v[126:127]
	v_pk_mul_f32 v[62:63], v[62:63], v[114:115]
	v_pk_mul_f32 v[58:59], v[58:59], v[118:119]
	v_pk_mul_f32 v[54:55], v[54:55], v[122:123]
	v_pk_mul_f32 v[64:65], v[64:65], v[116:117]
	v_pk_mul_f32 v[60:61], v[60:61], v[120:121]
	v_pk_mul_f32 v[56:57], v[56:57], v[124:125]
	v_pk_mul_f32 v[52:53], v[52:53], v[128:129]
	v_pk_mul_f32 v[50:51], v[50:51], v[126:127]
	v_pk_mul_f32 v[46:47], v[46:47], v[114:115]
	v_pk_mul_f32 v[42:43], v[42:43], v[118:119]
	v_pk_mul_f32 v[38:39], v[38:39], v[122:123]
	v_pk_mul_f32 v[48:49], v[48:49], v[116:117]
	v_pk_mul_f32 v[44:45], v[44:45], v[120:121]
	v_pk_mul_f32 v[40:41], v[40:41], v[124:125]
	v_pk_mul_f32 v[36:37], v[36:37], v[128:129]
	v_pk_mul_f32 v[34:35], v[34:35], v[126:127]
	v_pk_mul_f32 v[30:31], v[30:31], v[114:115]
	v_pk_mul_f32 v[26:27], v[26:27], v[118:119]
	v_pk_mul_f32 v[22:23], v[22:23], v[122:123]
	v_pk_mul_f32 v[32:33], v[32:33], v[116:117]
	v_pk_mul_f32 v[28:29], v[28:29], v[120:121]
	v_pk_mul_f32 v[24:25], v[24:25], v[124:125]
	v_pk_mul_f32 v[20:21], v[20:21], v[128:129]
	v_pk_mul_f32 v[18:19], v[18:19], v[126:127]

; #define LAS __attribute__((address_space(3)))
; __device__ __forceinline__ void phase_attn(const Params& p, int l, unsigned char* smem) {
;     ...
;     if (kind == 0) {
;         const int nlat = 16 * 16, nctx = need_ctx ? 16 : 0;
;         for (int li = xj; li < nlat + nctx; li += xn) {
;             int head, qb; const bool isctx = li >= nlat;
;             if (!isctx) { qb = li & 15; head = li >> 4; } else { qb = 0; head = li - nlat; }
;             const int kh = head >> 2;
;             const bf16_t* Qu = p.q + (((size_t)b * 16 + head) * TT + (isctx ? 0 : CTXL + qb * 256)) * 64;
;             const bf16_t* Kh = p.k + ((size_t)b * 4 + kh) * TT * 64;
;             const bf16_t* Vh = p.vt + ((size_t)b * 4 + kh) * TT * 64;
;             const size_t grow0 = isctx ? (size_t)MLAT + b * CTXL : (size_t)b * SEQ + qb * 256;
;             attn_a::attn_unit<8>(Qu, Kh, Vh, isctx ? 4 : TT / 64, p.sz + grow0 * D + head * 64, p.og + grow0 * D + head * 64, (char*)smem);
;         }
;     } else if (kind == 1) {
;         const int nlat = 16 * 16, nctx = need_ctx ? 16 : 0;
;         LAS float* rpbL = (LAS float*)((LAS unsigned char*)smem + 90112);
;         for (int li = xj; li < nlat + nctx; li += xn) {
.LBB0_760:
	s_setprio 0
	v_readlane_b32 s36, v254, 25
	s_movk_i32 s52, 0xe000
	s_andn2_b64 vcc, exec, s[4:5]
	v_readlane_b32 s37, v254, 26
	v_readlane_b32 s38, v254, 27
	v_readlane_b32 s39, v254, 28
	v_readlane_b32 s40, v254, 29
	v_readlane_b32 s41, v254, 30
	s_mov_b32 s53, -1
	v_readlane_b32 s68, v254, 59
	v_readlane_b32 s33, v254, 62
	v_readlane_b32 s42, v254, 31
	v_readlane_b32 s43, v254, 32
	v_readlane_b32 s44, v254, 33
	v_readlane_b32 s45, v254, 34
	v_readlane_b32 s46, v254, 35
	v_readlane_b32 s47, v254, 36
	v_readlane_b32 s48, v254, 37
	v_readlane_b32 s49, v254, 38
	v_readlane_b32 s50, v254, 39
	v_readlane_b32 s51, v254, 40
	s_cbranch_vccnz .LBB0_762
	v_readlane_b32 s4, v254, 60
	v_readlane_b32 s5, v254, 61
	s_and_b64 s[4:5], s[4:5], exec
	s_movk_i32 s4, 0x110
	s_cselect_b32 s20, 0x100, s4
	v_readlane_b32 s21, v254, 21
	s_cmp_ge_u32 s21, s20
	s_cbranch_scc0 .LBB0_838

;     __device__ __forceinline__ void operator()(const f32x4 (&acc)[2][2][4][2], const pg8::Unit& u, int wr, int wc, int fr, int fq) const {
;     ...
;         const float* src = l == 0 ? (isctx ? ctx + (size_t)(row0 - MLAT) * D : x + (size_t)row0 * D) : (isctx ? xb + (size_t)(row0 - MLAT) * D : out + (size_t)row0 * D);
;         float* dstp = isctx ? xb + (size_t)(row0 - MLAT) * D : out + (size_t)row0 * D;
; #pragma unroll
;         for (int ai = 0; ai < 2; ++ai)
; #pragma unroll
;             for (int m = 0; m < 4; ++m) {
;                 const size_t ro = (size_t)(ai * 128 + wr * 64 + m * 16 + fr) * D + n0;
;                 f32x4 xv[2][2];
; #pragma unroll
;                 for (int bj = 0; bj < 2; ++bj)
; #pragma unroll
;                     for (int n = 0; n < 2; ++n) xv[bj][n] = *(const f32x4*)(src + ro + bj * 128 + n * 16);
; #pragma unroll
;                 for (int bj = 0; bj < 2; ++bj)
; #pragma unroll
;                     for (int n = 0; n < 2; ++n) *(f32x4*)(dstp + ro + bj * 128 + n * 16) = xv[bj][n] + g4[bj][n] * acc[ai][bj][m][n];
;             }
.LBB0_833:
	s_lshl_b64 s[28:29], s[36:37], 12
	s_add_u32 s28, s26, s28
	s_addc_u32 s29, s27, s29
	v_readlane_b32 s52, v253, 32
	s_ashr_i32 s17, s30, 31
	s_add_i32 s19, s30, 0xffff8000
	v_readlane_b32 s53, v253, 33
	v_readlane_b32 s54, v253, 34
	v_readlane_b32 s55, v253, 35
	v_readlane_b32 s56, v253, 36
	v_readlane_b32 s57, v253, 37
	v_readlane_b32 s58, v253, 38
	v_readlane_b32 s59, v253, 39
	v_readlane_b32 s60, v253, 40
	v_readlane_b32 s61, v253, 41
	s_and_b64 s[26:27], s[34:35], exec
	v_readlane_b32 s62, v253, 42
	v_readlane_b32 s63, v253, 43
	v_readlane_b32 s64, v253, 44
	v_readlane_b32 s65, v253, 45
	v_readlane_b32 s66, v253, 46
	v_readlane_b32 s67, v253, 47
	s_mov_b64 s[52:53], s[60:61]
	s_cselect_b32 s27, 0, s17
	s_cselect_b32 s26, s19, s30
	s_mov_b64 s[54:55], s[62:63]
	s_mov_b64 s[56:57], s[64:65]
	s_cselect_b32 s17, s57, s55
	s_cselect_b32 s19, s56, s54
	s_lshl_b64 s[26:27], s[26:27], 12
	s_add_u32 s26, s19, s26
	s_addc_u32 s27, s17, s27
	s_andn2_b64 vcc, exec, s[24:25]
	s_mov_b64 s[58:59], s[66:67]
	v_lshl_add_u64 v[250:251], v[150:151], 0, v[170:171]
	v_lshlrev_b64 v[250:251], 2, v[250:251]
	v_lshl_add_u64 v[190:191], s[28:29], 0, v[250:251]
	global_load_dwordx4 v[174:177], v[190:191], off
	global_load_dwordx4 v[178:181], v[190:191], off offset:64
	global_load_dwordx4 v[182:185], v[190:191], off offset:512
	global_load_dwordx4 v[186:189], v[190:191], off offset:576
	v_lshl_add_u64 v[250:251], v[152:153], 0, v[170:171]
	v_lshlrev_b64 v[250:251], 2, v[250:251]
	v_lshl_add_u64 v[190:191], s[28:29], 0, v[250:251]
	global_load_dwordx4 v[192:195], v[190:191], off
	global_load_dwordx4 v[196:199], v[190:191], off offset:64
	global_load_dwordx4 v[200:203], v[190:191], off offset:512
	global_load_dwordx4 v[204:207], v[190:191], off offset:576
	v_lshl_add_u64 v[250:251], v[154:155], 0, v[170:171]
	v_lshlrev_b64 v[250:251], 2, v[250:251]
	v_lshl_add_u64 v[190:191], s[28:29], 0, v[250:251]
	global_load_dwordx4 v[208:211], v[190:191], off
	global_load_dwordx4 v[212:215], v[190:191], off offset:64
	global_load_dwordx4 v[216:219], v[190:191], off offset:512
	global_load_dwordx4 v[220:223], v[190:191], off offset:576
	v_lshl_add_u64 v[250:251], v[156:157], 0, v[170:171]
	v_lshlrev_b64 v[250:251], 2, v[250:251]
	v_lshl_add_u64 v[190:191], s[28:29], 0, v[250:251]
	global_load_dwordx4 v[224:227], v[190:191], off
	global_load_dwordx4 v[228:231], v[190:191], off offset:64
	global_load_dwordx4 v[240:243], v[190:191], off offset:512
	global_load_dwordx4 v[244:247], v[190:191], off offset:576
	v_lshl_add_u64 v[250:251], v[150:151], 0, v[170:171]
	v_lshlrev_b64 v[250:251], 2, v[250:251]
	v_lshl_add_u64 v[248:249], s[26:27], 0, v[250:251]
	s_waitcnt vmcnt(12)
	v_pk_fma_f32 v[146:147], v[146:147], v[106:107], v[174:175]
	v_pk_fma_f32 v[148:149], v[148:149], v[108:109], v[176:177]
	v_pk_fma_f32 v[142:143], v[142:143], v[102:103], v[178:179]
	v_pk_fma_f32 v[144:145], v[144:145], v[104:105], v[180:181]
	v_pk_fma_f32 v[138:139], v[138:139], v[98:99], v[182:183]
	v_pk_fma_f32 v[140:141], v[140:141], v[100:101], v[184:185]
	v_pk_fma_f32 v[134:135], v[134:135], v[94:95], v[186:187]
	v_pk_fma_f32 v[136:137], v[136:137], v[96:97], v[188:189]
	global_store_dwordx4 v[248:249], v[146:149], off
	global_store_dwordx4 v[248:249], v[142:145], off offset:64
	global_store_dwordx4 v[248:249], v[138:141], off offset:512
	global_store_dwordx4 v[248:249], v[134:137], off offset:576
	v_lshl_add_u64 v[250:251], v[158:159], 0, v[170:171]
	v_lshlrev_b64 v[250:251], 2, v[250:251]
	v_lshl_add_u64 v[190:191], s[28:29], 0, v[250:251]
	global_load_dwordx4 v[146:149], v[190:191], off
	global_load_dwordx4 v[142:145], v[190:191], off offset:64
	global_load_dwordx4 v[138:141], v[190:191], off offset:512
	global_load_dwordx4 v[134:137], v[190:191], off offset:576
	v_lshl_add_u64 v[250:251], v[152:153], 0, v[170:171]
	v_lshlrev_b64 v[250:251], 2, v[250:251]
	v_lshl_add_u64 v[232:233], s[26:27], 0, v[250:251]
	s_waitcnt vmcnt(16)
	v_pk_fma_f32 v[130:131], v[130:131], v[106:107], v[192:193]
	v_pk_fma_f32 v[132:133], v[132:133], v[108:109], v[194:195]
	v_pk_fma_f32 v[126:127], v[126:127], v[102:103], v[196:197]
	v_pk_fma_f32 v[128:129], v[128:129], v[104:105], v[198:199]
	v_pk_fma_f32 v[122:123], v[122:123], v[98:99], v[200:201]
	v_pk_fma_f32 v[124:125], v[124:125], v[100:101], v[202:203]
	v_pk_fma_f32 v[118:119], v[118:119], v[94:95], v[204:205]
	v_pk_fma_f32 v[120:121], v[120:121], v[96:97], v[206:207]
	global_store_dwordx4 v[232:233], v[130:133], off
	global_store_dwordx4 v[232:233], v[126:129], off offset:64
	global_store_dwordx4 v[232:233], v[122:125], off offset:512
	global_store_dwordx4 v[232:233], v[118:121], off offset:576
	v_lshl_add_u64 v[250:251], v[160:161], 0, v[170:171]
	v_lshlrev_b64 v[250:251], 2, v[250:251]
	v_lshl_add_u64 v[190:191], s[28:29], 0, v[250:251]
	global_load_dwordx4 v[130:133], v[190:191], off
	global_load_dwordx4 v[126:129], v[190:191], off offset:64
	global_load_dwordx4 v[122:125], v[190:191], off offset:512
	global_load_dwordx4 v[118:121], v[190:191], off offset:576
	v_lshl_add_u64 v[250:251], v[154:155], 0, v[170:171]
	v_lshlrev_b64 v[250:251], 2, v[250:251]
	v_lshl_add_u64 v[248:249], s[26:27], 0, v[250:251]
	s_waitcnt vmcnt(20)
;     __device__ __forceinline__ void operator()(const f32x4 (&acc)[2][2][4][2], const pg8::Unit& u, int wr, int wc, int fr, int fq) const {
;     ...
; #pragma unroll
;         for (int ai = 0; ai < 2; ++ai)
; #pragma unroll
;             for (int m = 0; m < 4; ++m) {
;                 const size_t ro = (size_t)(ai * 128 + wr * 64 + m * 16 + fr) * D + n0;
;                 f32x4 xv[2][2];
; #pragma unroll
;                 for (int bj = 0; bj < 2; ++bj)
; #pragma unroll
;                     for (int n = 0; n < 2; ++n) xv[bj][n] = *(const f32x4*)(src + ro + bj * 128 + n * 16);
; #pragma unroll
;                 for (int bj = 0; bj < 2; ++bj)
; #pragma unroll
;                     for (int n = 0; n < 2; ++n) *(f32x4*)(dstp + ro + bj * 128 + n * 16) = xv[bj][n] + g4[bj][n] * acc[ai][bj][m][n];
;             }
	v_pk_fma_f32 v[114:115], v[114:115], v[106:107], v[208:209]
	v_pk_fma_f32 v[116:117], v[116:117], v[108:109], v[210:211]
	v_pk_fma_f32 v[110:111], v[110:111], v[102:103], v[212:213]
	v_pk_fma_f32 v[112:113], v[112:113], v[104:105], v[214:215]
	v_pk_fma_f32 v[90:91], v[90:91], v[98:99], v[216:217]
	v_pk_fma_f32 v[92:93], v[92:93], v[100:101], v[218:219]
	v_pk_fma_f32 v[86:87], v[86:87], v[94:95], v[220:221]
	v_pk_fma_f32 v[88:89], v[88:89], v[96:97], v[222:223]
	global_store_dwordx4 v[248:249], v[114:117], off
	global_store_dwordx4 v[248:249], v[110:113], off offset:64
	global_store_dwordx4 v[248:249], v[90:93], off offset:512
	global_store_dwordx4 v[248:249], v[86:89], off offset:576
	v_lshl_add_u64 v[250:251], v[162:163], 0, v[170:171]
	v_lshlrev_b64 v[250:251], 2, v[250:251]
	v_lshl_add_u64 v[190:191], s[28:29], 0, v[250:251]
	global_load_dwordx4 v[114:117], v[190:191], off
	global_load_dwordx4 v[110:113], v[190:191], off offset:64
	global_load_dwordx4 v[90:93], v[190:191], off offset:512
	global_load_dwordx4 v[86:89], v[190:191], off offset:576
	v_lshl_add_u64 v[250:251], v[156:157], 0, v[170:171]
	v_lshlrev_b64 v[250:251], 2, v[250:251]
	v_lshl_add_u64 v[232:233], s[26:27], 0, v[250:251]
	s_waitcnt vmcnt(24)
	v_pk_fma_f32 v[82:83], v[82:83], v[106:107], v[224:225]
	v_pk_fma_f32 v[84:85], v[84:85], v[108:109], v[226:227]
	v_pk_fma_f32 v[78:79], v[78:79], v[102:103], v[228:229]
	v_pk_fma_f32 v[80:81], v[80:81], v[104:105], v[230:231]
	v_pk_fma_f32 v[74:75], v[74:75], v[98:99], v[240:241]
	v_pk_fma_f32 v[76:77], v[76:77], v[100:101], v[242:243]
	v_pk_fma_f32 v[70:71], v[70:71], v[94:95], v[244:245]
	v_pk_fma_f32 v[72:73], v[72:73], v[96:97], v[246:247]
	global_store_dwordx4 v[232:233], v[82:85], off
	global_store_dwordx4 v[232:233], v[78:81], off offset:64
	global_store_dwordx4 v[232:233], v[74:77], off offset:512
	global_store_dwordx4 v[232:233], v[70:73], off offset:576
	v_lshl_add_u64 v[250:251], v[164:165], 0, v[170:171]
	v_lshlrev_b64 v[250:251], 2, v[250:251]
	v_lshl_add_u64 v[190:191], s[28:29], 0, v[250:251]
	global_load_dwordx4 v[82:85], v[190:191], off
	global_load_dwordx4 v[78:81], v[190:191], off offset:64
	global_load_dwordx4 v[74:77], v[190:191], off offset:512
	global_load_dwordx4 v[70:73], v[190:191], off offset:576
	v_lshl_add_u64 v[250:251], v[158:159], 0, v[170:171]
	v_lshlrev_b64 v[250:251], 2, v[250:251]
	v_lshl_add_u64 v[248:249], s[26:27], 0, v[250:251]
	s_waitcnt vmcnt(24)
	v_pk_fma_f32 v[66:67], v[66:67], v[106:107], v[146:147]
	v_pk_fma_f32 v[68:69], v[68:69], v[108:109], v[148:149]
	v_pk_fma_f32 v[62:63], v[62:63], v[102:103], v[142:143]
	v_pk_fma_f32 v[64:65], v[64:65], v[104:105], v[144:145]
	v_pk_fma_f32 v[58:59], v[58:59], v[98:99], v[138:139]
	v_pk_fma_f32 v[60:61], v[60:61], v[100:101], v[140:141]
	v_pk_fma_f32 v[54:55], v[54:55], v[94:95], v[134:135]
	v_pk_fma_f32 v[56:57], v[56:57], v[96:97], v[136:137]
	global_store_dwordx4 v[248:249], v[66:69], off
	global_store_dwordx4 v[248:249], v[62:65], off offset:64
	global_store_dwordx4 v[248:249], v[58:61], off offset:512
	global_store_dwordx4 v[248:249], v[54:57], off offset:576
	v_lshl_add_u64 v[250:251], v[160:161], 0, v[170:171]
	v_lshlrev_b64 v[250:251], 2, v[250:251]
	v_lshl_add_u64 v[232:233], s[26:27], 0, v[250:251]
	s_waitcnt vmcnt(20)
	v_pk_fma_f32 v[50:51], v[50:51], v[106:107], v[130:131]
	v_pk_fma_f32 v[52:53], v[52:53], v[108:109], v[132:133]
	v_pk_fma_f32 v[46:47], v[46:47], v[102:103], v[126:127]
	v_pk_fma_f32 v[48:49], v[48:49], v[104:105], v[128:129]
	v_pk_fma_f32 v[42:43], v[42:43], v[98:99], v[122:123]
	v_pk_fma_f32 v[44:45], v[44:45], v[100:101], v[124:125]
	v_pk_fma_f32 v[38:39], v[38:39], v[94:95], v[118:119]
	v_pk_fma_f32 v[40:41], v[40:41], v[96:97], v[120:121]
	global_store_dwordx4 v[232:233], v[50:53], off
	global_store_dwordx4 v[232:233], v[46:49], off offset:64
	global_store_dwordx4 v[232:233], v[42:45], off offset:512
	global_store_dwordx4 v[232:233], v[38:41], off offset:576
	v_lshl_add_u64 v[250:251], v[162:163], 0, v[170:171]
	v_lshlrev_b64 v[250:251], 2, v[250:251]
	v_lshl_add_u64 v[248:249], s[26:27], 0, v[250:251]
	s_waitcnt vmcnt(16)
	v_pk_fma_f32 v[34:35], v[34:35], v[106:107], v[114:115]
	v_pk_fma_f32 v[36:37], v[36:37], v[108:109], v[116:117]
	v_pk_fma_f32 v[30:31], v[30:31], v[102:103], v[110:111]
	v_pk_fma_f32 v[32:33], v[32:33], v[104:105], v[112:113]
	v_pk_fma_f32 v[26:27], v[26:27], v[98:99], v[90:91]
	v_pk_fma_f32 v[28:29], v[28:29], v[100:101], v[92:93]
	v_pk_fma_f32 v[22:23], v[22:23], v[94:95], v[86:87]
	v_pk_fma_f32 v[24:25], v[24:25], v[96:97], v[88:89]
	global_store_dwordx4 v[248:249], v[34:37], off
	global_store_dwordx4 v[248:249], v[30:33], off offset:64
	global_store_dwordx4 v[248:249], v[26:29], off offset:512
	global_store_dwordx4 v[248:249], v[22:25], off offset:576
	v_lshl_add_u64 v[250:251], v[164:165], 0, v[170:171]
	v_lshlrev_b64 v[250:251], 2, v[250:251]
	v_lshl_add_u64 v[232:233], s[26:27], 0, v[250:251]
	s_waitcnt vmcnt(12)
	v_pk_fma_f32 v[18:19], v[18:19], v[106:107], v[82:83]
	v_pk_fma_f32 v[20:21], v[20:21], v[108:109], v[84:85]
	v_pk_fma_f32 v[10:11], v[10:11], v[102:103], v[78:79]
	v_pk_fma_f32 v[12:13], v[12:13], v[104:105], v[80:81]
	v_pk_fma_f32 v[6:7], v[6:7], v[98:99], v[74:75]
	v_pk_fma_f32 v[8:9], v[8:9], v[100:101], v[76:77]
	v_pk_fma_f32 v[2:3], v[2:3], v[94:95], v[70:71]
	v_pk_fma_f32 v[4:5], v[4:5], v[96:97], v[72:73]
	global_store_dwordx4 v[232:233], v[18:21], off
	global_store_dwordx4 v[232:233], v[10:13], off offset:64
	global_store_dwordx4 v[232:233], v[6:9], off offset:512
	global_store_dwordx4 v[232:233], v[2:5], off offset:576
	s_mov_b64 s[26:27], -1
	s_cbranch_vccnz .LBB0_814
	s_andn2_b64 vcc, exec, s[12:13]
	s_cbranch_vccnz .LBB0_813
	s_barrier
	s_branch .LBB0_813

.LBB0_840:
	v_add_u32_e32 v192, s8, v204
	ds_read_b64_tr_b16 v[182:183], v192 offset:24576
	ds_read_b64_tr_b16 v[184:185], v192 offset:25088
	s_waitcnt lgkmcnt(9)
	v_mfma_f32_32x32x16_bf16 v[114:129], v[178:181], v[146:149], v[50:65]
	v_add_f32_e32 v212, v82, v83
	v_cvt_pk_bf16_f32 v134, v82, v83
	v_add_f32_e32 v213, v84, v85
	v_cvt_pk_bf16_f32 v135, v84, v85
	v_add_f32_e32 v212, v86, v212
	v_add_f32_e32 v213, v87, v213
	ds_read_b64_tr_b16 v[178:179], v192 offset:28672
	ds_read_b64_tr_b16 v[180:181], v192 offset:29184
	s_waitcnt lgkmcnt(10)
	v_mfma_f32_32x32x16_bf16 v[98:113], v[174:177], v[146:149], v[50:65]
	v_add_f32_e32 v212, v88, v212
	v_cvt_pk_bf16_f32 v136, v86, v87
	v_add_f32_e32 v213, v89, v213
	v_cvt_pk_bf16_f32 v137, v88, v89
	v_add_f32_e32 v212, v90, v212
	v_add_f32_e32 v213, v91, v213
	ds_read_b64_tr_b16 v[82:83], v192 offset:25600
	ds_read_b64_tr_b16 v[84:85], v192 offset:26112
	s_waitcnt lgkmcnt(11)
	v_mfma_f32_32x32x16_bf16 v[114:129], v[170:173], v[142:145], v[114:129]
	v_add_f32_e32 v212, v92, v212
	v_cvt_pk_bf16_f32 v10, v90, v91
	v_add_f32_e32 v213, v93, v213
	v_cvt_pk_bf16_f32 v11, v92, v93
	v_add_f32_e32 v212, v94, v212
	v_add_f32_e32 v213, v95, v213
	ds_read_b64_tr_b16 v[86:87], v192 offset:29696
	ds_read_b64_tr_b16 v[88:89], v192 offset:30208
	s_waitcnt lgkmcnt(12)
	v_mfma_f32_32x32x16_bf16 v[98:113], v[166:169], v[142:145], v[98:113]
	v_add_f32_e32 v212, v96, v212
	v_cvt_pk_bf16_f32 v12, v94, v95
	v_add_f32_e32 v213, v97, v213
	v_cvt_pk_bf16_f32 v13, v96, v97
	v_add_f32_e32 v212, v66, v212
	v_add_f32_e32 v213, v67, v213
	ds_read_b64_tr_b16 v[90:91], v192 offset:26624
	ds_read_b64_tr_b16 v[92:93], v192 offset:27136
	s_waitcnt lgkmcnt(13)
	v_mfma_f32_32x32x16_bf16 v[114:129], v[162:165], v[138:141], v[114:129]
	v_add_f32_e32 v212, v68, v212
	v_cvt_pk_bf16_f32 v6, v66, v67
	v_add_f32_e32 v213, v69, v213
	v_cvt_pk_bf16_f32 v7, v68, v69
	v_add_f32_e32 v212, v70, v212
	v_add_f32_e32 v213, v71, v213
	ds_read_b64_tr_b16 v[66:67], v192 offset:30720
	ds_read_b64_tr_b16 v[68:69], v192 offset:31232
	s_waitcnt lgkmcnt(14)
	v_mfma_f32_32x32x16_bf16 v[98:113], v[158:161], v[138:141], v[98:113]
	v_add_f32_e32 v212, v72, v212
	v_cvt_pk_bf16_f32 v8, v70, v71
	v_add_f32_e32 v213, v73, v213
	v_cvt_pk_bf16_f32 v9, v72, v73
	v_add_f32_e32 v212, v74, v212
	v_add_f32_e32 v213, v75, v213
	ds_read_b64_tr_b16 v[70:71], v192 offset:27648
	ds_read_b64_tr_b16 v[72:73], v192 offset:28160
	s_waitcnt lgkmcnt(14)
	v_mfma_f32_32x32x16_bf16 v[114:129], v[154:157], v[130:133], v[114:129]
	v_add_f32_e32 v212, v76, v212
	v_cvt_pk_bf16_f32 v2, v74, v75
	v_add_f32_e32 v213, v77, v213
	v_cvt_pk_bf16_f32 v3, v76, v77
	v_add_f32_e32 v212, v78, v212
	v_add_f32_e32 v213, v79, v213
	ds_read_b64_tr_b16 v[74:75], v192 offset:31744
	ds_read_b64_tr_b16 v[76:77], v192 offset:32256
	v_mfma_f32_32x32x16_bf16 v[98:113], v[150:153], v[130:133], v[98:113]
	v_add_f32_e32 v212, v80, v212
	v_cvt_pk_bf16_f32 v4, v78, v79
	v_add_f32_e32 v213, v81, v213
	v_cvt_pk_bf16_f32 v5, v80, v81
	s_add_u32 s38, s34, s52
	s_addc_u32 s39, s35, s53
	s_add_i32 s8, s16, s26
	s_mov_b32 m0, s8
	s_nop 0
	global_load_lds_dwordx4 v208, s[38:39]
	s_add_u32 s40, s36, s52
	s_addc_u32 s41, s37, s53
	s_add_i32 s8, s14, s27
	s_mov_b32 m0, s8
	s_nop 0
	global_load_lds_dwordx4 v210, s[40:41]
	v_max3_f32 v78, v114, v115, v116
	v_max3_f32 v78, v78, v117, v118
	v_max3_f32 v79, v98, v99, v100
	v_max3_f32 v78, v78, v119, v120
	v_max3_f32 v79, v79, v101, v102
	v_max3_f32 v78, v78, v121, v122
	v_max3_f32 v79, v79, v103, v104
	v_max3_f32 v78, v78, v123, v124
	v_max3_f32 v79, v79, v105, v106
	v_max3_f32 v78, v78, v125, v126
	v_max3_f32 v79, v79, v107, v108
	v_max3_f32 v78, v78, v127, v128
	v_max3_f32 v79, v79, v109, v110
	v_max3_f32 v79, v79, v111, v112
	v_max3_f32 v78, v78, v129, v113
	v_max_f32_e32 v78, v78, v79
	v_mov_b32_e32 v79, v78
	s_nop 1
	v_permlane32_swap_b32_e32 v78, v79
	v_max_f32_e32 v78, v78, v79
	v_cmp_lt_f32_e32 vcc, s84, v78
	s_cmp_lg_u64 vcc, 0
	v_add_f32_e32 v212, v212, v213
	v_add_f32_e32 v192, v206, v212
	s_cselect_b64 s[8:9], -1, 0
	s_cbranch_vccnz .LBB0_848

.LBB0_843:
	s_add_i32 s8, s14, 0x2000
	s_cmpk_lg_i32 s14, 0x4000
	s_cselect_b32 s28, s8, 0
	v_add_u32_e32 v194, s16, v204
	ds_read_b64_tr_b16 v[154:155], v194 offset:24576
	ds_read_b64_tr_b16 v[156:157], v194 offset:25088
	s_waitcnt lgkmcnt(9)
	v_mfma_f32_32x32x16_bf16 v[82:97], v[78:81], v[146:149], v[50:65]
	v_add_f32_e32 v212, v114, v115
	v_cvt_pk_bf16_f32 v134, v114, v115
	v_add_f32_e32 v213, v116, v117
	v_cvt_pk_bf16_f32 v135, v116, v117
	v_add_f32_e32 v212, v118, v212
	v_add_f32_e32 v213, v119, v213
	ds_read_b64_tr_b16 v[150:151], v194 offset:28672
	ds_read_b64_tr_b16 v[152:153], v194 offset:29184
	s_waitcnt lgkmcnt(10)
	v_mfma_f32_32x32x16_bf16 v[66:81], v[178:181], v[146:149], v[50:65]
	v_add_f32_e32 v212, v120, v212
	v_cvt_pk_bf16_f32 v136, v118, v119
	v_add_f32_e32 v213, v121, v213
	v_cvt_pk_bf16_f32 v137, v120, v121
	v_add_f32_e32 v212, v122, v212
	v_add_f32_e32 v213, v123, v213
	ds_read_b64_tr_b16 v[114:115], v194 offset:25600
	ds_read_b64_tr_b16 v[116:117], v194 offset:26112
	s_waitcnt lgkmcnt(11)
	v_mfma_f32_32x32x16_bf16 v[82:97], v[182:185], v[142:145], v[82:97]
	v_add_f32_e32 v212, v124, v212
	v_cvt_pk_bf16_f32 v10, v122, v123
	v_add_f32_e32 v213, v125, v213
	v_cvt_pk_bf16_f32 v11, v124, v125
	v_add_f32_e32 v212, v126, v212
	v_add_f32_e32 v213, v127, v213
	ds_read_b64_tr_b16 v[118:119], v194 offset:29696
	ds_read_b64_tr_b16 v[120:121], v194 offset:30208
	s_waitcnt lgkmcnt(12)
	v_mfma_f32_32x32x16_bf16 v[66:81], v[174:177], v[142:145], v[66:81]
	v_add_f32_e32 v212, v128, v212
	v_cvt_pk_bf16_f32 v12, v126, v127
	v_add_f32_e32 v213, v129, v213
	v_cvt_pk_bf16_f32 v13, v128, v129
	v_add_f32_e32 v212, v98, v212
	v_add_f32_e32 v213, v99, v213
	ds_read_b64_tr_b16 v[122:123], v194 offset:26624
	ds_read_b64_tr_b16 v[124:125], v194 offset:27136
	s_waitcnt lgkmcnt(13)
	v_mfma_f32_32x32x16_bf16 v[82:97], v[170:173], v[138:141], v[82:97]
	v_add_f32_e32 v212, v100, v212
	v_cvt_pk_bf16_f32 v6, v98, v99
	v_add_f32_e32 v213, v101, v213
	v_cvt_pk_bf16_f32 v7, v100, v101
	v_add_f32_e32 v212, v102, v212
	v_add_f32_e32 v213, v103, v213
	ds_read_b64_tr_b16 v[98:99], v194 offset:30720
	ds_read_b64_tr_b16 v[100:101], v194 offset:31232
	s_waitcnt lgkmcnt(14)
	v_mfma_f32_32x32x16_bf16 v[66:81], v[166:169], v[138:141], v[66:81]
	v_add_f32_e32 v212, v104, v212
	v_cvt_pk_bf16_f32 v8, v102, v103
	v_add_f32_e32 v213, v105, v213
	v_cvt_pk_bf16_f32 v9, v104, v105
	v_add_f32_e32 v212, v106, v212
	v_add_f32_e32 v213, v107, v213
	ds_read_b64_tr_b16 v[102:103], v194 offset:27648
	ds_read_b64_tr_b16 v[104:105], v194 offset:28160
	s_waitcnt lgkmcnt(14)
	v_mfma_f32_32x32x16_bf16 v[82:97], v[162:165], v[130:133], v[82:97]
	v_add_f32_e32 v212, v108, v212
	v_cvt_pk_bf16_f32 v2, v106, v107
	v_add_f32_e32 v213, v109, v213
	v_cvt_pk_bf16_f32 v3, v108, v109
	v_add_f32_e32 v212, v110, v212
	v_add_f32_e32 v213, v111, v213
	ds_read_b64_tr_b16 v[106:107], v194 offset:31744
	ds_read_b64_tr_b16 v[108:109], v194 offset:32256
	v_mfma_f32_32x32x16_bf16 v[66:81], v[158:161], v[130:133], v[66:81]
	v_add_f32_e32 v212, v112, v212
	v_cvt_pk_bf16_f32 v4, v110, v111
	v_add_f32_e32 v213, v113, v213
	v_cvt_pk_bf16_f32 v5, v112, v113
	s_add_i32 s8, s14, s26
	s_mov_b32 m0, s8
	s_nop 0
	global_load_lds_dwordx4 v208, s[34:35]
	s_add_i32 s8, s28, s27
	s_mov_b32 m0, s8
	s_nop 0
	global_load_lds_dwordx4 v210, s[36:37]
	v_max3_f32 v110, v82, v83, v84
	v_max3_f32 v110, v110, v85, v86
	v_max3_f32 v111, v66, v67, v68
	v_max3_f32 v110, v110, v87, v88
	v_max3_f32 v111, v111, v69, v70
	v_max3_f32 v110, v110, v89, v90
	v_max3_f32 v111, v111, v71, v72
	v_max3_f32 v110, v110, v91, v92
	v_max3_f32 v111, v111, v73, v74
	v_max3_f32 v110, v110, v93, v94
	v_max3_f32 v111, v111, v75, v76
	v_max3_f32 v110, v110, v95, v96
	v_max3_f32 v111, v111, v77, v78
	v_max3_f32 v111, v111, v79, v80
	v_max3_f32 v110, v110, v97, v81
	v_max_f32_e32 v110, v110, v111
	v_mov_b32_e32 v111, v110
	s_nop 1
	v_permlane32_swap_b32_e32 v110, v111
	v_max_f32_e32 v110, v110, v111
	v_cmp_lt_f32_e32 vcc, s84, v110
	s_cmp_lg_u64 vcc, 0
	v_add_f32_e32 v212, v212, v213
	v_add_f32_e32 v206, v192, v212
	s_cselect_b64 s[8:9], -1, 0
	s_cbranch_vccnz .LBB0_851
